# attention loop: two-chain row max, permlane32 swap instead of ds_bpermute, base increments moved into the MFMA-to-VALU wait slot
# baseline (speedup 1.0000x reference)
.LBB0_265:
	v_lshlrev_b32_e32 v150, 3, v34
	v_exp_f32_e32 v34, v2
	v_exp_f32_e32 v35, v18
	v_exp_f32_e32 v18, v3
	v_exp_f32_e32 v19, v19
	s_waitcnt lgkmcnt(0)
	v_exp_f32_e32 v36, v4
	v_exp_f32_e32 v37, v20
	v_exp_f32_e32 v20, v5
	v_exp_f32_e32 v21, v21
	v_pk_add_f32 v[2:3], v[34:35], 0 op_sel_hi:[1,0]
	v_exp_f32_e32 v38, v6
	v_exp_f32_e32 v39, v22
	v_pk_add_f32 v[2:3], v[2:3], v[18:19]
	v_exp_f32_e32 v6, v7
	v_exp_f32_e32 v7, v23
	v_pk_add_f32 v[2:3], v[36:37], v[2:3]
	v_exp_f32_e32 v22, v8
	v_exp_f32_e32 v23, v24
	v_pk_add_f32 v[2:3], v[20:21], v[2:3]
	v_exp_f32_e32 v8, v9
	v_exp_f32_e32 v9, v25
	v_pk_add_f32 v[2:3], v[38:39], v[2:3]
	v_exp_f32_e32 v24, v10
	v_exp_f32_e32 v25, v26
	v_pk_add_f32 v[2:3], v[6:7], v[2:3]
	v_exp_f32_e32 v10, v11
	v_exp_f32_e32 v11, v27
	v_pk_add_f32 v[2:3], v[22:23], v[2:3]
	v_exp_f32_e32 v26, v12
	v_exp_f32_e32 v27, v28
	v_pk_add_f32 v[2:3], v[8:9], v[2:3]
	v_exp_f32_e32 v12, v13
	v_exp_f32_e32 v13, v29
	v_pk_add_f32 v[2:3], v[24:25], v[2:3]
	v_exp_f32_e32 v28, v14
	v_exp_f32_e32 v29, v30
	v_pk_add_f32 v[2:3], v[10:11], v[2:3]
	v_exp_f32_e32 v14, v15
	v_exp_f32_e32 v15, v31
	v_pk_add_f32 v[2:3], v[26:27], v[2:3]
	v_exp_f32_e32 v30, v16
	v_exp_f32_e32 v31, v32
	v_pk_add_f32 v[2:3], v[12:13], v[2:3]
	v_exp_f32_e32 v16, v17
	v_exp_f32_e32 v17, v33
	v_pk_add_f32 v[2:3], v[28:29], v[2:3]
	v_and_b32_e32 v184, 63, v236
	v_pk_add_f32 v[2:3], v[14:15], v[2:3]
	v_ashrrev_i32_e32 v161, 31, v160
	v_pk_add_f32 v[2:3], v[30:31], v[2:3]
	v_cvt_pk_bf16_f32 v4, v38, v6
	v_pk_add_f32 v[128:129], v[16:17], v[2:3]
	v_cvt_pk_bf16_f32 v2, v34, v18
	v_cvt_pk_bf16_f32 v3, v36, v20
	v_cvt_pk_bf16_f32 v5, v22, v8
	v_cvt_pk_bf16_f32 v118, v24, v10
	v_cvt_pk_bf16_f32 v119, v26, v12
	v_cvt_pk_bf16_f32 v120, v28, v14
	v_cvt_pk_bf16_f32 v121, v30, v16
	v_cvt_pk_bf16_f32 v124, v35, v19
	v_cvt_pk_bf16_f32 v125, v37, v21
	v_cvt_pk_bf16_f32 v126, v39, v7
	v_cvt_pk_bf16_f32 v127, v23, v9
	v_cvt_pk_bf16_f32 v156, v25, v11
	v_cvt_pk_bf16_f32 v157, v27, v13
	v_cvt_pk_bf16_f32 v158, v29, v15
	v_cvt_pk_bf16_f32 v159, v31, v17
	s_ashr_i32 s5, s4, 31
	s_setprio 1
	v_sub_u32_e32 v6, v146, v150
	v_mad_u32_u24 v10, v116, s70, v6
	v_add_u32_e32 v11, 0x4800, v10
	ds_read2_b64 v[6:9], v11 offset1:2
	v_add_u32_e32 v132, 0x7800, v10
	ds_read2_b64 v[162:165], v132 offset0:100 offset1:102
	v_mul_u32_u24_e32 v186, 0x88, v116
	v_add_f32_e32 v116, v128, v129
	v_add_f32_e32 v185, 0, v116
	s_waitcnt lgkmcnt(1)
	v_mfma_f32_32x32x16_bf16 v[50:65], v[6:9], v[2:5], 0
	ds_read2_b64 v[6:9], v11 offset0:4 offset1:6
	s_waitcnt lgkmcnt(0)
	v_mfma_f32_32x32x16_bf16 v[50:65], v[6:9], v[118:121], v[50:65]
	ds_read2_b64 v[6:9], v11 offset0:8 offset1:10
	s_waitcnt lgkmcnt(0)
	v_mfma_f32_32x32x16_bf16 v[50:65], v[6:9], v[124:127], v[50:65]
	ds_read2_b64 v[6:9], v11 offset0:12 offset1:14
	v_add_u32_e32 v11, 0x5800, v10
	s_waitcnt lgkmcnt(0)
	v_mfma_f32_32x32x16_bf16 v[50:65], v[6:9], v[156:159], v[50:65]
	ds_read2_b64 v[6:9], v11 offset0:32 offset1:34
	s_waitcnt lgkmcnt(0)
	v_mfma_f32_32x32x16_bf16 v[34:49], v[6:9], v[2:5], 0
	ds_read2_b64 v[6:9], v11 offset0:36 offset1:38
	s_waitcnt lgkmcnt(0)
	v_mfma_f32_32x32x16_bf16 v[34:49], v[6:9], v[118:121], v[34:49]
	ds_read2_b64 v[6:9], v11 offset0:40 offset1:42
	s_waitcnt lgkmcnt(0)
	v_mfma_f32_32x32x16_bf16 v[34:49], v[6:9], v[124:127], v[34:49]
	ds_read2_b64 v[6:9], v11 offset0:44 offset1:46
	v_add_u32_e32 v11, 0x6800, v10
	s_waitcnt lgkmcnt(0)
	v_mfma_f32_32x32x16_bf16 v[34:49], v[6:9], v[156:159], v[34:49]
	ds_read2_b64 v[6:9], v11 offset0:64 offset1:66
	s_waitcnt lgkmcnt(0)
	v_mfma_f32_32x32x16_bf16 v[18:33], v[6:9], v[2:5], 0
	ds_read2_b64 v[6:9], v11 offset0:68 offset1:70
	s_waitcnt lgkmcnt(0)
	v_mfma_f32_32x32x16_bf16 v[18:33], v[6:9], v[118:121], v[18:33]
	ds_read2_b64 v[6:9], v11 offset0:72 offset1:74
	s_waitcnt lgkmcnt(0)
	v_mfma_f32_32x32x16_bf16 v[18:33], v[6:9], v[124:127], v[18:33]
	ds_read2_b64 v[6:9], v11 offset0:76 offset1:78
	s_waitcnt lgkmcnt(0)
	v_mfma_f32_32x32x16_bf16 v[18:33], v[6:9], v[156:159], v[18:33]
	ds_read2_b64 v[6:9], v132 offset0:96 offset1:98
	s_waitcnt lgkmcnt(0)
	v_mfma_f32_32x32x16_bf16 v[2:17], v[6:9], v[2:5], 0
	v_mfma_f32_32x32x16_bf16 v[2:17], v[162:165], v[118:121], v[2:17]
	ds_read2_b64 v[118:121], v132 offset0:104 offset1:106
	s_waitcnt lgkmcnt(0)
	v_mfma_f32_32x32x16_bf16 v[2:17], v[118:121], v[124:127], v[2:17]
	ds_read2_b64 v[118:121], v132 offset0:108 offset1:110
	s_waitcnt lgkmcnt(0)
	v_mfma_f32_32x32x16_bf16 v[2:17], v[118:121], v[156:159], v[2:17]
	s_setprio 0
	s_waitcnt vmcnt(0)
	ds_write_b128 v117, v[94:97] offset:35840
	ds_write_b128 v117, v[90:93] offset:40448
	ds_write_b128 v117, v[86:89] offset:45056
	ds_write_b128 v117, v[82:85] offset:49664
	v_add_u32_e32 v82, 0xd400, v0
	ds_write2_b64 v82, v[78:79], v[80:81] offset1:1
	v_add_u32_e32 v78, 0xe500, v0
	v_add_u32_e32 v0, 0xf600, v0
	ds_write2_b64 v0, v[70:71], v[72:73] offset1:1
	v_add_u32_e32 v0, 0x3300, v82
	s_movk_i32 s1, 0x5000
	ds_write2_b64 v0, v[66:67], v[68:69] offset1:1
	v_add_co_u32_e32 v66, vcc, s1, v114
	ds_write2_b64 v78, v[74:75], v[76:77] offset1:1
	s_nop 0
	v_addc_co_u32_e32 v67, vcc, 0, v115, vcc
	global_load_dwordx4 v[114:117], v[66:67], off offset:-4096
	global_load_dwordx4 v[118:121], v[66:67], off
	v_add_co_u32_e32 v66, vcc, s1, v122
	v_readlane_b32 s36, v252, 4
	s_nop 0
	v_addc_co_u32_e32 v67, vcc, 0, v123, vcc
	global_load_dwordx4 v[122:125], v[66:67], off offset:-4096
	global_load_dwordx4 v[126:129], v[66:67], off
	s_nop 0
	global_load_dwordx4 v[130:133], v[130:131], off offset:256
	s_nop 0
	global_load_dwordx4 v[134:137], v[134:135], off offset:256
	s_nop 0
	global_load_dwordx4 v[138:141], v[138:139], off offset:256
	s_nop 0
	global_load_dwordx4 v[142:145], v[142:143], off offset:256
	v_readlane_b32 s50, v252, 18
	v_readlane_b32 s51, v252, 19
	s_add_u32 s26, s50, s21
	v_lshlrev_b32_e32 v66, 4, v236
	s_addc_u32 s27, s51, s20
	s_lshl_b64 s[4:5], s[4:5], 8
	v_and_b32_e32 v66, 0x1f80, v66
	v_mov_b32_e32 v67, v1
	s_or_b32 s20, s4, 0x80
	v_lshl_add_u64 v[156:157], s[26:27], 0, v[66:67]
	s_mul_i32 s24, s13, s5
	s_mul_hi_u32 s26, s13, s20
	s_add_i32 s24, s26, s24
	s_mul_i32 s26, s13, s20
	s_add_u32 s26, s50, s26
	s_addc_u32 s27, s51, s24
	v_lshl_add_u64 v[158:159], s[26:27], 0, v[66:67]
	v_lshlrev_b64 v[66:67], 1, v[160:161]
	s_mov_b32 s21, s5
	v_lshl_add_u64 v[68:69], s[4:5], 0, v[66:67]
	v_mov_b64_e32 v[70:71], s[50:51]
	v_lshl_add_u64 v[72:73], v[68:69], 0, 64
	v_lshl_add_u64 v[66:67], s[20:21], 0, v[66:67]
	v_mad_u64_u32 v[160:161], s[4:5], s13, v68, v[70:71]
	v_mad_u64_u32 v[162:163], s[4:5], s13, v72, v[70:71]
	v_mad_u64_u32 v[164:165], s[4:5], s13, v66, v[70:71]
	s_mov_b64 s[4:5], 0xc0
	v_mad_i32_i24 v165, s13, v67, v165
	v_lshl_add_u64 v[66:67], v[68:69], 0, s[4:5]
	v_and_b32_e32 v0, 7, v236
	v_mad_u64_u32 v[166:167], s[4:5], s13, v66, v[70:71]
	v_lshlrev_b32_e32 v0, 4, v0
	v_mad_i32_i24 v161, s13, v69, v161
	v_mad_i32_i24 v163, s13, v73, v163
	v_mad_i32_i24 v167, s13, v67, v167
	v_mov_b32_e32 v250, 0xe429800
	v_mov_b32_e32 v251, 0
	v_lshl_add_u64 v[156:157], v[156:157], 0, v[0:1]
	v_lshl_add_u64 v[156:157], v[156:157], 0, v[250:251]
	v_lshl_add_u64 v[158:159], v[158:159], 0, v[0:1]
	v_lshl_add_u64 v[158:159], v[158:159], 0, v[250:251]
	v_mov_b32_e32 v250, 0xeca4f80
	v_lshl_add_u64 v[160:161], v[160:161], 0, v[0:1]
	v_lshl_add_u64 v[160:161], v[160:161], 0, v[250:251]
	v_lshl_add_u64 v[162:163], v[162:163], 0, v[0:1]
	v_lshl_add_u64 v[162:163], v[162:163], 0, v[250:251]
	v_lshl_add_u64 v[164:165], v[164:165], 0, v[0:1]
	v_lshl_add_u64 v[164:165], v[164:165], 0, v[250:251]
	v_lshl_add_u64 v[166:167], v[166:167], 0, v[0:1]
	v_lshl_add_u64 v[166:167], v[166:167], 0, v[250:251]
	s_mov_b32 s4, 3
	s_waitcnt lgkmcnt(0)
	s_barrier
	v_readlane_b32 s37, v252, 5
	v_readlane_b32 s38, v252, 6
	v_readlane_b32 s39, v252, 7
	v_readlane_b32 s40, v252, 8
	v_readlane_b32 s41, v252, 9
	v_readlane_b32 s42, v252, 10
	v_readlane_b32 s43, v252, 11
	v_readlane_b32 s44, v252, 12
	v_readlane_b32 s45, v252, 13
	v_readlane_b32 s46, v252, 14
	v_readlane_b32 s47, v252, 15
	v_readlane_b32 s48, v252, 16
	v_readlane_b32 s49, v252, 17
	s_branch .LBB0_267
.LBB0_266:
	s_add_i32 s4, s4, 1
	s_add_i32 s5, s12, s4
	s_cmp_eq_u32 s5, 2
	v_add_f32_e32 v185, v185, v238
	s_waitcnt lgkmcnt(0)
	s_barrier
	s_cbranch_scc1 .LBB0_272
.LBB0_267:
	s_bitcmp1_b32 s4, 0
	s_cselect_b32 s5, 0x8c00, 0
	v_xor_b32_e32 v66, 0x80000000, v154
	s_setprio 1
	v_or_b32_e32 v67, s5, v146
	v_add_u32_e32 v172, v67, v183
	ds_read_b128 v[206:209], v172
	ds_read_b128 v[210:213], v172 offset:4608
	ds_read_b128 v[222:225], v172 offset:32
	ds_read_b128 v[238:241], v172 offset:4640
	ds_read_b128 v[242:245], v172 offset:64
	v_mov_b32_e32 v67, v66
	v_mov_b32_e32 v68, v66
	v_mov_b32_e32 v69, v66
	v_mov_b32_e32 v70, v66
	v_mov_b32_e32 v71, v66
	v_mov_b32_e32 v72, v66
	v_mov_b32_e32 v73, v66
	v_mov_b32_e32 v74, v66
	v_mov_b32_e32 v75, v66
	v_mov_b32_e32 v76, v66
	v_mov_b32_e32 v77, v66
	v_mov_b32_e32 v78, v66
	v_mov_b32_e32 v79, v66
	v_mov_b32_e32 v80, v66
	v_mov_b32_e32 v81, v66
	s_waitcnt lgkmcnt(4)
	s_nop 0
	v_mfma_f32_32x32x16_bf16 v[82:97], v[206:209], v[98:101], v[66:81]
	ds_read_b128 v[206:209], v172 offset:4672
	s_waitcnt lgkmcnt(4)
	v_mfma_f32_32x32x16_bf16 v[66:81], v[210:213], v[98:101], v[66:81]
	ds_read_b128 v[210:213], v172 offset:96
	s_waitcnt lgkmcnt(4)
	v_mfma_f32_32x32x16_bf16 v[82:97], v[222:225], v[102:105], v[82:97]
	ds_read_b128 v[222:225], v172 offset:4704
	s_waitcnt lgkmcnt(4)
	v_mfma_f32_32x32x16_bf16 v[66:81], v[238:241], v[102:105], v[66:81]
	s_waitcnt lgkmcnt(3)
	v_mfma_f32_32x32x16_bf16 v[82:97], v[242:245], v[106:109], v[82:97]
	s_waitcnt lgkmcnt(2)
	v_mfma_f32_32x32x16_bf16 v[66:81], v[206:209], v[106:109], v[66:81]
	s_waitcnt lgkmcnt(1)
	v_mfma_f32_32x32x16_bf16 v[82:97], v[210:213], v[110:113], v[82:97]
	s_waitcnt lgkmcnt(0)
	v_mfma_f32_32x32x16_bf16 v[66:81], v[222:225], v[110:113], v[66:81]
	s_setprio 0
	s_mov_b64 s[20:21], 0x2000
	v_lshl_add_u64 v[156:157], v[156:157], 0, s[20:21]
	v_lshl_add_u64 v[158:159], v[158:159], 0, s[20:21]
	s_mov_b64 s[20:21], 0x80
	v_lshl_add_u64 v[160:161], v[160:161], 0, s[20:21]
	v_lshl_add_u64 v[162:163], v[162:163], 0, s[20:21]
	v_lshl_add_u64 v[164:165], v[164:165], 0, s[20:21]
	v_lshl_add_u64 v[166:167], v[166:167], 0, s[20:21]
	s_nop 3
	v_max3_f32 v168, v66, v67, v68
	v_max3_f32 v169, v69, v70, v71
	v_max3_f32 v168, v168, v72, v73
	v_max3_f32 v169, v169, v74, v75
	v_max3_f32 v168, v168, v76, v77
	v_max3_f32 v169, v169, v78, v79
	v_max3_f32 v168, v168, v80, v81
	v_max3_f32 v169, v169, v82, v83
	v_max3_f32 v168, v168, v84, v85
	v_max3_f32 v169, v169, v86, v87
	v_max3_f32 v168, v168, v88, v89
	v_max3_f32 v169, v169, v90, v91
	v_max3_f32 v168, v168, v92, v93
	v_max3_f32 v169, v169, v94, v95
	v_max3_f32 v168, v168, v96, v97
	v_max_f32_e32 v168, v168, v169
	v_mov_b32_e32 v169, v168
	s_mov_b32 s20, 0x41000000
	s_nop 1
	v_permlane32_swap_b32_e32 v168, v169
	v_max_f32_e32 v168, v168, v169
	v_cmp_lt_f32_e32 vcc, s20, v168
	s_cbranch_vccz .LBB0_269
	v_max_f32_e32 v168, v168, v168
	v_max_f32_e32 v168, 0, v168
	v_add_f32_e32 v169, v154, v168
	v_sub_f32_e32 v154, v169, v154
	v_mov_b32_e32 v170, v82
	v_mov_b32_e32 v171, v66
	v_mov_b32_e32 v82, v83
	v_mov_b32_e32 v83, v84
	v_mov_b32_e32 v66, v67
	v_mov_b32_e32 v67, v68
	v_pk_add_f32 v[172:173], v[82:83], v[154:155] op_sel_hi:[1,0] neg_lo:[0,1] neg_hi:[0,1]
	v_pk_add_f32 v[82:83], v[66:67], v[154:155] op_sel_hi:[1,0] neg_lo:[0,1] neg_hi:[0,1]
	v_mov_b32_e32 v66, v85
	v_mov_b32_e32 v67, v86
	v_pk_add_f32 v[174:175], v[66:67], v[154:155] op_sel_hi:[1,0] neg_lo:[0,1] neg_hi:[0,1]
	v_mov_b32_e32 v66, v69
	v_mov_b32_e32 v67, v70
	v_pk_add_f32 v[84:85], v[66:67], v[154:155] op_sel_hi:[1,0] neg_lo:[0,1] neg_hi:[0,1]
	v_mov_b32_e32 v66, v87
	v_mov_b32_e32 v67, v88
	v_pk_add_f32 v[176:177], v[66:67], v[154:155] op_sel_hi:[1,0] neg_lo:[0,1] neg_hi:[0,1]
	v_mov_b32_e32 v66, v71
	v_mov_b32_e32 v67, v72
	v_pk_add_f32 v[86:87], v[66:67], v[154:155] op_sel_hi:[1,0] neg_lo:[0,1] neg_hi:[0,1]
	v_mov_b32_e32 v66, v89
	v_mov_b32_e32 v67, v90
	v_pk_add_f32 v[178:179], v[66:67], v[154:155] op_sel_hi:[1,0] neg_lo:[0,1] neg_hi:[0,1]
	v_mov_b32_e32 v66, v73
	v_mov_b32_e32 v67, v74
	v_pk_add_f32 v[88:89], v[66:67], v[154:155] op_sel_hi:[1,0] neg_lo:[0,1] neg_hi:[0,1]
	v_mov_b32_e32 v66, v91
	v_mov_b32_e32 v67, v92
	v_pk_add_f32 v[180:181], v[66:67], v[154:155] op_sel_hi:[1,0] neg_lo:[0,1] neg_hi:[0,1]
	v_mov_b32_e32 v66, v75
	v_mov_b32_e32 v67, v76
	v_pk_add_f32 v[90:91], v[66:67], v[154:155] op_sel_hi:[1,0] neg_lo:[0,1] neg_hi:[0,1]
	v_mov_b32_e32 v66, v93
	v_mov_b32_e32 v67, v94
	v_exp_f32_e64 v168, -v154
	v_pk_add_f32 v[188:189], v[66:67], v[154:155] op_sel_hi:[1,0] neg_lo:[0,1] neg_hi:[0,1]
	v_mov_b32_e32 v66, v77
	v_mov_b32_e32 v67, v78
	v_pk_add_f32 v[92:93], v[66:67], v[154:155] op_sel_hi:[1,0] neg_lo:[0,1] neg_hi:[0,1]
	v_mov_b32_e32 v66, v95
	v_mov_b32_e32 v67, v96
	v_pk_add_f32 v[190:191], v[66:67], v[154:155] op_sel_hi:[1,0] neg_lo:[0,1] neg_hi:[0,1]
	v_mov_b32_e32 v66, v79
	v_mov_b32_e32 v67, v80
	v_pk_add_f32 v[170:171], v[170:171], v[154:155] op_sel_hi:[1,0] neg_lo:[0,1] neg_hi:[0,1]
	v_pk_add_f32 v[94:95], v[66:67], v[154:155] op_sel_hi:[1,0] neg_lo:[0,1] neg_hi:[0,1]
	v_pk_mul_f32 v[64:65], v[64:65], v[168:169] op_sel_hi:[1,0]
	v_pk_mul_f32 v[62:63], v[62:63], v[168:169] op_sel_hi:[1,0]
	v_pk_mul_f32 v[60:61], v[60:61], v[168:169] op_sel_hi:[1,0]
	v_pk_mul_f32 v[58:59], v[58:59], v[168:169] op_sel_hi:[1,0]
	v_pk_mul_f32 v[56:57], v[56:57], v[168:169] op_sel_hi:[1,0]
	v_pk_mul_f32 v[54:55], v[54:55], v[168:169] op_sel_hi:[1,0]
	v_pk_mul_f32 v[52:53], v[52:53], v[168:169] op_sel_hi:[1,0]
	v_pk_mul_f32 v[50:51], v[50:51], v[168:169] op_sel_hi:[1,0]
	v_pk_mul_f32 v[48:49], v[48:49], v[168:169] op_sel_hi:[1,0]
	v_pk_mul_f32 v[46:47], v[46:47], v[168:169] op_sel_hi:[1,0]
	v_pk_mul_f32 v[44:45], v[44:45], v[168:169] op_sel_hi:[1,0]
	v_pk_mul_f32 v[42:43], v[42:43], v[168:169] op_sel_hi:[1,0]
	v_pk_mul_f32 v[40:41], v[40:41], v[168:169] op_sel_hi:[1,0]
	v_pk_mul_f32 v[38:39], v[38:39], v[168:169] op_sel_hi:[1,0]
	v_pk_mul_f32 v[36:37], v[36:37], v[168:169] op_sel_hi:[1,0]
	v_pk_mul_f32 v[34:35], v[34:35], v[168:169] op_sel_hi:[1,0]
	v_pk_mul_f32 v[32:33], v[32:33], v[168:169] op_sel_hi:[1,0]
	v_pk_mul_f32 v[30:31], v[30:31], v[168:169] op_sel_hi:[1,0]
	v_pk_mul_f32 v[28:29], v[28:29], v[168:169] op_sel_hi:[1,0]
	v_pk_mul_f32 v[26:27], v[26:27], v[168:169] op_sel_hi:[1,0]
	v_pk_mul_f32 v[24:25], v[24:25], v[168:169] op_sel_hi:[1,0]
	v_pk_mul_f32 v[22:23], v[22:23], v[168:169] op_sel_hi:[1,0]
	v_pk_mul_f32 v[20:21], v[20:21], v[168:169] op_sel_hi:[1,0]
	v_pk_mul_f32 v[18:19], v[18:19], v[168:169] op_sel_hi:[1,0]
	v_pk_mul_f32 v[16:17], v[16:17], v[168:169] op_sel_hi:[1,0]
	v_pk_mul_f32 v[14:15], v[14:15], v[168:169] op_sel_hi:[1,0]
	v_pk_mul_f32 v[12:13], v[12:13], v[168:169] op_sel_hi:[1,0]
	v_pk_mul_f32 v[10:11], v[10:11], v[168:169] op_sel_hi:[1,0]
	v_pk_mul_f32 v[8:9], v[8:9], v[168:169] op_sel_hi:[1,0]
	v_pk_mul_f32 v[6:7], v[6:7], v[168:169] op_sel_hi:[1,0]
	v_pk_mul_f32 v[4:5], v[4:5], v[168:169] op_sel_hi:[1,0]
	v_pk_mul_f32 v[2:3], v[2:3], v[168:169] op_sel_hi:[1,0]
	v_sub_f32_e32 v97, v97, v154
	v_sub_f32_e32 v81, v81, v154
	v_mul_f32_e32 v185, v185, v168
	v_mov_b32_e32 v154, v169
	v_mov_b32_e32 v67, v82
	v_mov_b32_e32 v68, v83
	v_mov_b32_e32 v69, v84
	v_mov_b32_e32 v70, v85
	v_mov_b32_e32 v71, v86
	v_mov_b32_e32 v72, v87
	v_mov_b32_e32 v73, v88
	v_mov_b32_e32 v74, v89
	v_mov_b32_e32 v75, v90
	v_mov_b32_e32 v76, v91
	v_mov_b32_e32 v77, v92
	v_mov_b32_e32 v78, v93
	v_mov_b32_e32 v79, v94
	v_mov_b32_e32 v80, v95
	v_mov_b32_e32 v83, v172
	v_mov_b32_e32 v84, v173
	v_mov_b32_e32 v85, v174
	v_mov_b32_e32 v86, v175
	v_mov_b32_e32 v87, v176
	v_mov_b32_e32 v88, v177
	v_mov_b32_e32 v89, v178
	v_mov_b32_e32 v90, v179
	v_mov_b32_e32 v91, v180
	v_mov_b32_e32 v92, v181
	v_mov_b32_e32 v93, v188
	v_mov_b32_e32 v94, v189
	v_mov_b32_e32 v95, v190
	v_mov_b32_e32 v96, v191
	v_mov_b32_e32 v82, v170
	v_mov_b32_e32 v66, v171
